# attention phase: static s_setprio 1 for waves 0-3 instead (per-half A/B of the static raise)
# speedup vs baseline: 1.0054x; 1.0054x over previous
; #define ARG_IN(i) argp(i)
; __global__ void __launch_bounds__(NWAVES * 64, 2) mk_fwd(Args) {
;     ...
;                     __syncthreads();
;                     for (int uu = vcu_; uu < 256; uu += G_) { const int bh = uu >> 4, s = uu & 15, b = bh >> 3, r = bh & 7;
;     ...
;                         for (int i = 0; i < 2; ++i) { const int h = __builtin_amdgcn_readfirstlane(hmap[i ? 7 - r : r]);
;                             attn_body::attn_unit<0, 24>(b, h, i ? s : 31 - s, (const abf*)(SL + 2 * SLOT_E), (const abf*)(SL + 6 * SLOT_E), (const abf*)(SL + 7 * SLOT_E), (abf*)(SL + 2 * SLOT_E), (char*)lds_raw, (const float*)(ws + WS_CUM), (const float*)(ws + WS_BT), ARG_IN(9) + l * 256); }
;     ...
;                         for (int i = 0; i < 2; ++i)
;                             attn_body::attn_unit<1, 8>(b, r, i ? s : 31 - s, (const abf*)(SL + 0 * SLOT_E), (const abf*)(SL + 3 * SLOT_E), (const abf*)(SL + 4 * SLOT_E), (abf*)(SL + 0 * SLOT_E), (char*)lds_raw, ARG_IN(10) + (size_t)(l * 8 + r) * 257, nullptr, nullptr);
.LBB0_721:
	s_or_b64 exec, exec, s[8:9]
	s_andn2_b64 vcc, exec, s[12:13]
	s_waitcnt lgkmcnt(0)
	s_barrier
	s_cbranch_vccnz .LBB0_965
	s_add_u32 s0, s10, 0x5600000
	v_writelane_b32 v255, s0, 34
	s_addc_u32 s0, s11, 0
	v_writelane_b32 v255, s0, 35
	s_add_u32 s0, s10, 0x7600000
	v_writelane_b32 v255, s0, 36
	s_addc_u32 s0, s11, 0
	s_add_u32 s1, s10, 0xb600000
	s_addc_u32 s43, s11, 0
	s_add_u32 s59, s10, 0xc600000
	s_addc_u32 s89, s11, 0
	s_add_u32 s42, s10, 0x100000
	s_addc_u32 s82, s11, 0
	s_add_u32 s60, s10, 0x50000
	s_addc_u32 s61, s11, 0
	v_writelane_b32 v255, s1, 37
	s_add_u32 s1, s10, 0x8600000
	v_writelane_b32 v255, s1, 38
	s_addc_u32 s1, s11, 0
	v_writelane_b32 v255, s1, 39
	s_add_u32 s1, s10, 0x9600000
	v_writelane_b32 v255, s1, 40
	s_addc_u32 s1, s11, 0
	v_writelane_b32 v255, s1, 41
	s_add_u32 s1, s10, 0x101800
	v_writelane_b32 v255, s1, 42
	s_addc_u32 s1, s11, 0
	v_writelane_b32 v255, s1, 43
	v_writelane_b32 v255, s56, 44
	s_nop 1
	v_writelane_b32 v255, s57, 45
	v_readlane_b32 s1, v255, 4
	s_nop 3
	s_cmp_lt_u32 s1, 4
	s_cbranch_scc0 .Lmy_prio_done
	s_setprio 1
